# v66 + rw_prep unit prologue: previous-row values loaded with d16_hi loads, three serialised vmcnt(0) round trips removed (lever 2)
# baseline (speedup 1.0000x reference)
; __device__ __forceinline__ float bf2f(bf16 x) { return __uint_as_float(((unsigned)x) << 16); }
; __device__ __forceinline__ float zr_prev(const bf16* ZR, const float* sh0, int row, int col) {
;     if (row < MPR) return row == 0 ? 0.f : bf2f(ZR[(size_t)(row - 1) * LDZR + col]);
;     const int q = row - MPR, s = q >> 4, t = q & 15;
;     return t == 0 ? sh0[(size_t)s * DRIN + col] : bf2f(ZR[(size_t)(row - 1) * LDZR + col]);
; __device__ __forceinline__ void rw_prep(Frame& F) {
;     ...
;         const int col = h * 64 + lane;
;         const float mur = mu[col], muk = mu[2048 + col], muv = mu[4096 + col], kkw = F.in[I_KK][col], kaw = F.in[I_KA][col], rkw = F.in[I_RK][col];
;         float pr = zr_prev(ZR, sh0, row0, col), pk = zr_prev(ZR, sh0, row0, 2048 + col), pv = zr_prev(ZR, sh0, row0, 4096 + col);
.LBB0_917:
	s_load_dwordx2 s[22:23], s[74:75], 0x78
	s_load_dwordx2 s[24:25], s[74:75], 0xb8
	v_lshl_or_b32 v12, s10, 6, v178
	v_ashrrev_i32_e32 v13, 31, v12
	v_lshlrev_b64 v[6:7], 2, v[12:13]
	s_waitcnt vmcnt(3) lgkmcnt(0)
	v_lshl_add_u64 v[8:9], s[22:23], 0, v[6:7]
	v_add_co_u32_e32 v10, vcc, 0x2000, v8
	s_cmpk_gt_u32 s20, 0x3fff
	s_nop 0
	v_addc_co_u32_e32 v11, vcc, 0, v9, vcc
	v_add_co_u32_e32 v18, vcc, 0x4000, v8
	s_cselect_b64 s[22:23], -1, 0
	s_nop 0
	v_addc_co_u32_e32 v19, vcc, 0, v9, vcc
	global_load_dword v16, v[8:9], off
	global_load_dword v17, v[10:11], off
	s_nop 0
	global_load_dword v18, v[18:19], off
	v_lshl_add_u64 v[8:9], s[12:13], 0, v[6:7]
	global_load_dword v19, v[8:9], off
	v_lshl_add_u64 v[8:9], s[14:15], 0, v[6:7]
	v_lshl_add_u64 v[6:7], s[24:25], 0, v[6:7]
	global_load_dword v20, v[8:9], off
	global_load_dword v21, v[6:7], off
	s_mov_b64 s[24:25], -1
	s_and_b64 vcc, exec, s[22:23]
	s_cbranch_vccz .LBB0_922
	s_and_b32 s6, s20, 15
	s_cmp_lg_u32 s6, 0
	s_cbranch_scc0 .LBB0_925
	s_add_i32 s6, s20, -1
	s_mul_hi_u32 s11, s6, 0x3600
	s_mulk_i32 s6, 0x3600
	s_add_u32 s24, s18, s6
	s_addc_u32 s25, s19, s11
	v_lshl_add_u64 v[6:7], v[12:13], 1, s[24:25]
	v_mov_b32_e32 v76, 0
	global_load_short_d16_hi v76, v[6:7], off
	s_cbranch_execnz .LBB0_921

; __device__ __forceinline__ float bf2f(bf16 x) { return __uint_as_float(((unsigned)x) << 16); }
; __device__ __forceinline__ float zr_prev(const bf16* ZR, const float* sh0, int row, int col) {
;     if (row < MPR) return row == 0 ? 0.f : bf2f(ZR[(size_t)(row - 1) * LDZR + col]);
.LBB0_922:
	s_andn2_b64 vcc, exec, s[24:25]
	s_cbranch_vccnz .LBB0_927
	s_cmp_eq_u32 s20, 0
	s_cbranch_scc1 .LBB0_926
	s_add_i32 s6, s20, -1
	s_mul_hi_u32 s11, s6, 0x3600
	s_mulk_i32 s6, 0x3600
	s_add_u32 s24, s18, s6
	s_addc_u32 s25, s19, s11
	v_lshl_add_u64 v[6:7], v[12:13], 1, s[24:25]
	v_mov_b32_e32 v76, 0
	global_load_short_d16_hi v76, v[6:7], off
	s_branch .LBB0_927

; __device__ __forceinline__ float bf2f(bf16 x) { return __uint_as_float(((unsigned)x) << 16); }
; __device__ __forceinline__ float zr_prev(const bf16* ZR, const float* sh0, int row, int col) {
;     if (row < MPR) return row == 0 ? 0.f : bf2f(ZR[(size_t)(row - 1) * LDZR + col]);
;     const int q = row - MPR, s = q >> 4, t = q & 15;
;     return t == 0 ? sh0[(size_t)s * DRIN + col] : bf2f(ZR[(size_t)(row - 1) * LDZR + col]);
; __device__ __forceinline__ void rw_prep(Frame& F) {
;     ...
;         float pr = zr_prev(ZR, sh0, row0, col), pk = zr_prev(ZR, sh0, row0, 2048 + col), pv = zr_prev(ZR, sh0, row0, 4096 + col);
.LBB0_926:
	v_mov_b32_e32 v76, 0
.LBB0_927:
	v_add_u32_e32 v6, 0x800, v12
	v_ashrrev_i32_e32 v7, 31, v6
	s_mov_b64 s[24:25], -1
	s_and_b64 vcc, exec, s[22:23]
	s_cbranch_vccz .LBB0_932
	s_and_b32 s6, s20, 15
	s_cmp_lg_u32 s6, 0
	s_cbranch_scc0 .LBB0_935
	s_add_i32 s6, s20, -1
	s_mul_hi_u32 s11, s6, 0x3600
	s_mulk_i32 s6, 0x3600
	s_add_u32 s24, s18, s6
	s_addc_u32 s25, s19, s11
	v_lshl_add_u64 v[8:9], v[6:7], 1, s[24:25]
	v_mov_b32_e32 v81, 0
	global_load_short_d16_hi v81, v[8:9], off
	s_cbranch_execnz .LBB0_931

; __device__ __forceinline__ float bf2f(bf16 x) { return __uint_as_float(((unsigned)x) << 16); }
; __device__ __forceinline__ float zr_prev(const bf16* ZR, const float* sh0, int row, int col) {
;     if (row < MPR) return row == 0 ? 0.f : bf2f(ZR[(size_t)(row - 1) * LDZR + col]);
.LBB0_932:
	s_andn2_b64 vcc, exec, s[24:25]
	s_cbranch_vccnz .LBB0_937
	s_cmp_eq_u32 s20, 0
	s_cbranch_scc1 .LBB0_936
	s_add_i32 s6, s20, -1
	s_mul_hi_u32 s11, s6, 0x3600
	s_mulk_i32 s6, 0x3600
	s_add_u32 s24, s18, s6
	s_addc_u32 s25, s19, s11
	v_lshl_add_u64 v[6:7], v[6:7], 1, s[24:25]
	v_mov_b32_e32 v81, 0
	global_load_short_d16_hi v81, v[6:7], off
	s_branch .LBB0_937

; __device__ __forceinline__ float bf2f(bf16 x) { return __uint_as_float(((unsigned)x) << 16); }
; __device__ __forceinline__ float zr_prev(const bf16* ZR, const float* sh0, int row, int col) {
;     if (row < MPR) return row == 0 ? 0.f : bf2f(ZR[(size_t)(row - 1) * LDZR + col]);
;     const int q = row - MPR, s = q >> 4, t = q & 15;
;     return t == 0 ? sh0[(size_t)s * DRIN + col] : bf2f(ZR[(size_t)(row - 1) * LDZR + col]);
; __device__ __forceinline__ void rw_prep(Frame& F) {
;     ...
;         float pr = zr_prev(ZR, sh0, row0, col), pk = zr_prev(ZR, sh0, row0, 2048 + col), pv = zr_prev(ZR, sh0, row0, 4096 + col);
.LBB0_936:
	v_mov_b32_e32 v81, 0
.LBB0_937:
	v_add_u32_e32 v6, 0x1000, v12
	v_ashrrev_i32_e32 v7, 31, v6
	s_mov_b64 s[24:25], -1
	s_and_b64 vcc, exec, s[22:23]
	s_cbranch_vccz .LBB0_942
	s_and_b32 s6, s20, 15
	s_cmp_lg_u32 s6, 0
	s_cbranch_scc0 .LBB0_945
	s_add_i32 s6, s20, -1
	s_mul_hi_u32 s11, s6, 0x3600
	s_mulk_i32 s6, 0x3600
	s_add_u32 s22, s18, s6
	s_addc_u32 s23, s19, s11
	v_lshl_add_u64 v[8:9], v[6:7], 1, s[22:23]
	v_mov_b32_e32 v82, 0
	global_load_short_d16_hi v82, v[8:9], off
	s_cbranch_execnz .LBB0_941

; __device__ __forceinline__ float bf2f(bf16 x) { return __uint_as_float(((unsigned)x) << 16); }
; __device__ __forceinline__ float zr_prev(const bf16* ZR, const float* sh0, int row, int col) {
;     if (row < MPR) return row == 0 ? 0.f : bf2f(ZR[(size_t)(row - 1) * LDZR + col]);
.LBB0_942:
	s_andn2_b64 vcc, exec, s[24:25]
	s_cbranch_vccnz .LBB0_947
	s_cmp_eq_u32 s20, 0
	s_cbranch_scc1 .LBB0_946
	s_add_i32 s6, s20, -1
	s_mul_hi_u32 s11, s6, 0x3600
	s_mulk_i32 s6, 0x3600
	s_add_u32 s22, s18, s6
	s_addc_u32 s23, s19, s11
	v_lshl_add_u64 v[6:7], v[6:7], 1, s[22:23]
	v_mov_b32_e32 v82, 0
	global_load_short_d16_hi v82, v[6:7], off
	s_branch .LBB0_947

; __device__ __forceinline__ float bf2f(bf16 x) { return __uint_as_float(((unsigned)x) << 16); }
; __device__ __forceinline__ float zr_prev(const bf16* ZR, const float* sh0, int row, int col) {
;     if (row < MPR) return row == 0 ? 0.f : bf2f(ZR[(size_t)(row - 1) * LDZR + col]);
.LBB0_946:
	v_mov_b32_e32 v82, 0
